# Wo last-panel tail also 4-way K split on 16 WGs (bf16 partial tiles in WS_MXT summed in f32 by the row phase, same scheme the baseline uses for the down tail)
# speedup vs baseline: 1.0206x; 1.0080x over previous
; __device__ __forceinline__ KP kp_fresh(KP k) { asm volatile("" : "+s"(k)); return k; }
; __device__ __forceinline__ int tid_fresh(int wid) { return wid * 64 + lane_id(); }
; __global__ void __launch_bounds__(512, 2) hybrid_fwd(Params p_unused) {
;     ...
;             const int gpi = half == 0 ? 3 : 5; const bool hn = half == 0 ? true : (layer + 1 < DEPTH);
;             const int ntail = half == 1 ? 8 : 4;
;             if (bid < ntail) {
;                 const int ks = bid >> 2;
;                 unsigned char* ws = kp_fresh(kp0)->ws;
;                 pg8::Gemm gt = g; bf16* mxo = (bf16*)(ws + WS_MX);
;                 if (half == 1) { gt.A = g.A + ks * (DFF / 2); gt.Bt = g.Bt + ks * (DFF / 2); gt.K = DFF / 2; mxo = (bf16*)(ws + WS_MXT) + (size_t)ks * 256 * 1024 - (size_t)128 * 256 * 1024; }
;                 pg8::TailOrder S{128, 4, bid & 3};
;                 pg8::EpiStore E{mxo, 1024, (half == 0 && (layer & 1)) ? (const float*)(ws + WS_RSTD) : nullptr, 0.f, nullptr, nullptr, nullptr, LL};
;                 pg8::gemm_phase<pg8::EpiStore, pg8::TailOrder, true, true>(lds, gt, S, E, wid0);
;                 tail_barrier((unsigned*)kp_fresh(kp0)->ws + 3584 + 64 * (layer * 2 + half), tid_fresh(wid0), (unsigned)ntail);
;                 const int rpb = 256 / ntail;
;                 row_res(kp0, gpi, layer, hn, wid0, 128 * 256 + rpb * bid, 128 * 256 + rpb * bid + rpb, bid, 1, half == 1 ? 2 : 0, half == 0 && (layer & 1));
;             } else {
;                 row_res(kp0, gpi, layer, hn, wid0, 0, 128 * 256, ntail, G - ntail, 0, half == 0 && (layer & 1));
.LBB0_773:
	s_or_b64 exec, exec, s[2:3]
	s_and_b64 s[2:3], s[28:29], exec
	v_readlane_b32 s2, v255, 49
	v_readlane_b32 s3, v255, 50
	s_cselect_b32 s17, 3, 5
	s_nor_b64 s[34:35], s[2:3], s[28:29]
	v_readlane_b32 s2, v255, 51
	v_readlane_b32 s3, v255, 52
	s_and_b64 s[2:3], s[2:3], s[28:29]
	s_cselect_b32 s18, 4, 16
	s_cmp_ge_i32 s33, s18
	s_mov_b64 s[2:3], -1
	s_waitcnt lgkmcnt(0)
	s_barrier
	s_cbranch_scc0 .LBB0_822
	s_mov_b64 s[2:3], s[88:89]
	v_mbcnt_lo_u32_b32 v1, -1, 0
	v_mbcnt_hi_u32_b32 v1, -1, v1
	s_sub_i32 s4, s33, s18
	v_add_u32_e32 v2, s61, v1
	v_ashrrev_i32_e32 v2, 6, v2
	v_lshl_add_u32 v38, s4, 4, v2
	s_mov_b32 s4, 0x8000
	v_cmp_gt_i32_e32 vcc, s4, v38
	s_and_saveexec_b64 s[44:45], vcc
	s_cbranch_execz .LBB0_821
	s_load_dwordx4 s[8:11], s[2:3], 0x90
	v_readlane_b32 s4, v255, 51
	v_readlane_b32 s5, v255, 52
	s_and_b64 s[4:5], s[4:5], s[28:29]
	s_xor_b64 s[78:79], s[4:5], -1
	s_waitcnt lgkmcnt(0)
	s_add_u32 s92, s10, 0x180000
	s_addc_u32 s93, s11, 0
	s_lshl_b32 s4, s17, 3
	s_load_dwordx2 s[2:3], s[2:3], s4 offset:0x0
	v_readlane_b32 s4, v255, 53
	v_readlane_b32 s5, v255, 54
	v_and_b32_e32 v3, 63, v1
	s_sub_i32 s14, s38, s18
	s_lshl_b64 s[4:5], s[4:5], 2
	v_lshlrev_b32_e32 v4, 4, v3
	s_waitcnt lgkmcnt(0)
	s_add_u32 s4, s2, s4
	v_mov_b32_e32 v5, v0
	s_addc_u32 s5, s3, s5
	s_waitcnt vmcnt(2)
	v_lshl_add_u64 v[6:7], s[10:11], 0, v[4:5]
	s_mov_b64 s[2:3], 0x18f74000
	v_lshl_add_u64 v[42:43], v[6:7], 0, s[2:3]
	s_mov_b64 s[2:3], 0x10e74000
	v_lshl_add_u64 v[44:45], v[6:7], 0, s[2:3]
	v_bfe_u32 v6, v1, 5, 1
	v_lshlrev_b32_e64 v1, v6, 2
	v_lshlrev_b32_e64 v41, v6, 8
	v_lshlrev_b32_e32 v6, 2, v3
	s_lshl_b32 s46, s14, 4
	v_xor_b32_e32 v101, 0x80, v6
	v_xor_b32_e32 v102, 64, v6
	v_xor_b32_e32 v103, 32, v6
	v_xor_b32_e32 v104, 16, v6
	v_xor_b32_e32 v105, 8, v6
	v_xor_b32_e32 v106, 4, v6
	v_lshlrev_b32_e32 v6, 5, v3
	v_mov_b32_e32 v7, v0
	v_lshl_add_u64 v[46:47], s[4:5], 0, v[6:7]
	s_add_u32 s4, s10, 0x10e73800
	v_ashrrev_i32_e32 v39, 31, v38
	s_addc_u32 s5, s11, 0
	v_lshlrev_b64 v[6:7], 11, v[38:39]
	s_ashr_i32 s47, s46, 31
	v_or_b32_e32 v6, v6, v4
	s_lshl_b64 s[58:59], s[46:47], 11
	v_lshl_add_u64 v[48:49], s[4:5], 0, v[6:7]
	s_add_u32 s10, s10, 0x10e73c00
	v_lshl_add_u64 v[52:53], s[4:5], 0, v[4:5]
	v_readlane_b32 s4, v255, 31
	s_addc_u32 s11, s11, 0
	v_lshlrev_b32_e32 v40, 3, v3
	v_add_u32_e32 v2, s4, v2
	s_lshl_b32 s4, s18, 4
	v_cmp_eq_u32_e64 s[2:3], 0, v3
	v_lshl_add_u64 v[50:51], s[10:11], 0, v[6:7]
	v_subrev_u32_e32 v54, s4, v2
	v_lshl_add_u64 v[56:57], s[10:11], 0, v[4:5]
	s_mov_b64 s[10:11], 0
	s_branch .LBB0_778

; __device__ __forceinline__ KP kp_fresh(KP k) { asm volatile("" : "+s"(k)); return k; }
; __global__ void __launch_bounds__(512, 2) hybrid_fwd(Params p_unused) {
;     ...
;             if (bid < ntail) {
;                 const int ks = bid >> 2;
;                 unsigned char* ws = kp_fresh(kp0)->ws;
;                 pg8::Gemm gt = g; bf16* mxo = (bf16*)(ws + WS_MX);
;                 if (half == 1) { gt.A = g.A + ks * (DFF / 2); gt.Bt = g.Bt + ks * (DFF / 2); gt.K = DFF / 2; mxo = (bf16*)(ws + WS_MXT) + (size_t)ks * 256 * 1024 - (size_t)128 * 256 * 1024; }
;                 pg8::TailOrder S{128, 4, bid & 3};
;                 pg8::EpiStore E{mxo, 1024, (half == 0 && (layer & 1)) ? (const float*)(ws + WS_RSTD) : nullptr, 0.f, nullptr, nullptr, nullptr, LL};
;                 pg8::gemm_phase<pg8::EpiStore, pg8::TailOrder, true, true>(lds, gt, S, E, wid0);
.LBB0_822:
	s_andn2_b64 vcc, exec, s[2:3]
	s_cbranch_vccnz .LBB0_924
	s_mov_b64 s[2:3], s[88:89]
	s_load_dwordx2 s[2:3], s[2:3], 0x98
	s_waitcnt lgkmcnt(0)
	s_add_u32 s4, s2, 0x10e74000
	s_addc_u32 s5, s3, 0
	v_readlane_b32 s14, v255, 51
	v_readlane_b32 s15, v255, 52
	s_and_b64 vcc, s[14:15], s[28:29]
	s_cbranch_vccnz .LBB0_825
	s_and_b64 vcc, exec, s[24:25]
	s_cbranch_vccz .Ltl4_wo
	v_readlane_b32 s4, v255, 36
	v_readlane_b32 s5, v255, 37
	s_lshr_b32 s14, s33, 3
	s_lshl_b32 s14, s14, 7
	s_sub_i32 s14, 0x300, s14
	s_branch .Ltl4_join
.Ltl4_wo:
	s_lshr_b32 s4, s33, 2
	s_lshl_b32 s4, s4, 9
	s_mov_b32 s5, 0
	s_movk_i32 s14, 0x100
.Ltl4_join:
	s_add_u32 s1, s1, s4
	s_addc_u32 s6, s6, s5
	s_add_u32 s12, s12, s4
	s_addc_u32 s13, s13, s5
	v_readlane_b32 s4, v255, 9
	v_readlane_b32 s5, v255, 10
	s_add_u32 s4, s2, s4
	s_addc_u32 s5, s3, s5
	s_add_u32 s4, s4, 0xfc200000
	s_addc_u32 s5, s5, -1
	s_branch .LBB0_826

; __global__ void __launch_bounds__(512, 2) hybrid_fwd(Params p_unused) {
;     ...
;                 const int rpb = 256 / ntail;
;                 row_res(kp0, gpi, layer, hn, wid0, 128 * 256 + rpb * bid, 128 * 256 + rpb * bid + rpb, bid, 1, half == 1 ? 2 : 0, half == 0 && (layer & 1));
.LBB0_860:
	s_or_b64 exec, exec, s[2:3]
	s_mov_b64 s[2:3], s[88:89]
	s_barrier
	v_readlane_b32 s0, v255, 51
	v_readlane_b32 s1, v255, 52
	s_and_b64 s[0:1], s[0:1], s[28:29]
	v_mbcnt_lo_u32_b32 v1, -1, 0
	v_mbcnt_hi_u32_b32 v1, -1, v1
	s_cselect_b32 s0, 64, 16
	v_add_u32_e32 v2, s61, v1
	v_ashrrev_i32_e32 v2, 6, v2
	v_cmp_gt_i32_e32 vcc, s0, v2
	s_and_saveexec_b64 s[36:37], vcc
	s_cbranch_execz .LBB0_923
	v_readlane_b32 s4, v255, 51
	v_readlane_b32 s5, v255, 52
	s_and_b64 s[4:5], s[4:5], s[28:29]
	s_load_dwordx4 s[8:11], s[2:3], 0x90
	s_cselect_b32 s1, 6, 4
	s_mov_b64 s[26:27], s[4:5]
	s_lshl_b32 s1, s33, s1
	s_add_i32 s6, s1, 0x8000
	s_add_i32 s0, s6, s0
	s_xor_b64 s[28:29], s[4:5], -1
	s_waitcnt lgkmcnt(0)
	s_add_u32 s44, s10, 0x180000
	s_addc_u32 s45, s11, 0
	s_lshl_b32 s4, s17, 3
	s_load_dwordx2 s[2:3], s[2:3], s4 offset:0x0
	v_readlane_b32 s4, v255, 53
	v_readlane_b32 s5, v255, 54
	s_lshl_b64 s[4:5], s[4:5], 2
	v_and_b32_e32 v3, 63, v1
	s_waitcnt lgkmcnt(0)
	s_add_u32 s4, s2, s4
	v_lshlrev_b32_e32 v4, 4, v3
	v_mov_b32_e32 v5, v0
	s_addc_u32 s5, s3, s5
	v_lshl_add_u64 v[6:7], s[10:11], 0, v[4:5]
	s_mov_b64 s[2:3], 0x18f74000
	v_lshl_add_u64 v[42:43], v[6:7], 0, s[2:3]
	s_mov_b64 s[2:3], 0x200000
	v_lshl_add_u64 v[44:45], v[6:7], 0, s[2:3]
	s_mov_b64 s[2:3], 0x10e74000
	v_lshl_add_u64 v[46:47], v[6:7], 0, s[2:3]
	v_bfe_u32 v6, v1, 5, 1
	v_lshlrev_b32_e64 v1, v6, 2
	v_lshlrev_b32_e64 v41, v6, 8
	v_lshlrev_b32_e32 v6, 2, v3
	v_xor_b32_e32 v103, 0x80, v6
	v_xor_b32_e32 v104, 64, v6
	v_xor_b32_e32 v105, 32, v6
	v_xor_b32_e32 v106, 16, v6
	v_xor_b32_e32 v107, 8, v6
	v_xor_b32_e32 v108, 4, v6
	v_lshlrev_b32_e32 v6, 5, v3
	v_mov_b32_e32 v7, v0
	v_add_u32_e32 v38, s6, v2
	v_lshl_add_u64 v[48:49], s[4:5], 0, v[6:7]
	s_add_u32 s4, s10, 0x10e73800
	s_addc_u32 s5, s11, 0
	v_ashrrev_i32_e32 v39, 31, v38
	v_lshlrev_b64 v[6:7], 11, v[38:39]
	s_add_u32 s6, s10, 0x10e73c00
	v_or_b32_e32 v6, v6, v4
	s_addc_u32 s7, s11, 0
	v_add_u32_e32 v2, s1, v2
	v_lshlrev_b32_e32 v40, 3, v3
	v_cmp_eq_u32_e64 s[2:3], 0, v3
	v_lshl_add_u64 v[50:51], s[4:5], 0, v[6:7]
	v_lshl_add_u64 v[52:53], s[6:7], 0, v[6:7]
	v_lshl_add_u64 v[54:55], s[4:5], 0, v[4:5]
	v_add_u32_e32 v56, 0x8008, v2
	v_lshl_add_u64 v[58:59], s[6:7], 0, v[4:5]
	s_mov_b64 s[10:11], 0
	s_branch .LBB0_864
